# instruction selection: the main G1 epilogue's 16 silu blocks use packed f32 multiply/add around the exp and rcp (40 -> 28 VALU instructions per block)
# baseline (speedup 1.0000x reference)
.LBB0_60:
	s_mov_b32 s98, 0xbfb8aa3b
	s_mov_b32 s99, 0xbfb8aa3b
	s_lshl_b32 s4, s8, 8
	s_cmp_gt_i32 s8, 1
	s_mov_b32 s0, s50
	s_mov_b32 s89, 0
	s_cselect_b64 s[6:7], -1, 0
	s_cmp_lt_i32 s8, 2
	s_mov_b32 s93, 0
	s_cbranch_scc1 .LBB0_64
	s_cmpk_lt_u32 s4, 0x400
	s_mov_b32 s93, 1
	s_cbranch_scc1 .LBB0_64
	s_cmpk_lt_u32 s4, 0x500
	s_mov_b32 s93, 5
	s_cbranch_scc1 .LBB0_64
	s_cmp_eq_u32 s8, 9
	s_cselect_b32 s1, 3, 1
	s_cmpk_gt_u32 s4, 0x8ff
	s_cselect_b32 s1, s1, 2
	s_cmpk_gt_u32 s4, 0x6ff
	s_cselect_b32 s1, s1, 1
	s_cmpk_gt_u32 s4, 0x5ff
	s_cselect_b32 s93, s1, 0

.LBB0_92:
	v_pk_mul_f32 v[146:147], v[142:143], s[98:99]
	v_pk_mul_f32 v[148:149], v[138:139], s[98:99]
	v_pk_mul_f32 v[150:151], v[144:145], s[98:99]
	v_pk_mul_f32 v[152:153], v[140:141], s[98:99]
	v_exp_f32_e32 v146, v146
	v_exp_f32_e32 v147, v147
	v_exp_f32_e32 v148, v148
	v_exp_f32_e32 v149, v149
	v_exp_f32_e32 v150, v150
	v_exp_f32_e32 v151, v151
	v_exp_f32_e32 v152, v152
	v_exp_f32_e32 v153, v153
	v_pk_add_f32 v[146:147], v[146:147], 1.0 op_sel_hi:[1,0]
	v_pk_add_f32 v[148:149], v[148:149], 1.0 op_sel_hi:[1,0]
	v_pk_add_f32 v[150:151], v[150:151], 1.0 op_sel_hi:[1,0]
	v_pk_add_f32 v[152:153], v[152:153], 1.0 op_sel_hi:[1,0]
	v_rcp_f32_e32 v146, v146
	v_rcp_f32_e32 v147, v147
	v_rcp_f32_e32 v148, v148
	v_rcp_f32_e32 v149, v149
	v_rcp_f32_e32 v150, v150
	v_rcp_f32_e32 v151, v151
	v_rcp_f32_e32 v152, v152
	v_rcp_f32_e32 v153, v153
	s_nop 0
	v_pk_mul_f32 v[182:183], v[142:143], v[146:147]
	v_pk_mul_f32 v[186:187], v[138:139], v[148:149]
	v_pk_mul_f32 v[184:185], v[144:145], v[150:151]
	v_pk_mul_f32 v[188:189], v[140:141], v[152:153]

.LBB0_112:
	s_andn2_b64 vcc, exec, s[20:21]
	s_cbranch_vccnz .LBB0_114
	v_pk_mul_f32 v[138:139], v[134:135], s[98:99]
	v_pk_mul_f32 v[142:143], v[130:131], s[98:99]
	v_pk_mul_f32 v[140:141], v[136:137], s[98:99]
	v_pk_mul_f32 v[144:145], v[132:133], s[98:99]
	v_exp_f32_e32 v138, v138
	v_exp_f32_e32 v139, v139
	v_exp_f32_e32 v142, v142
	v_exp_f32_e32 v143, v143
	v_exp_f32_e32 v140, v140
	v_exp_f32_e32 v141, v141
	v_exp_f32_e32 v144, v144
	v_exp_f32_e32 v145, v145
	v_pk_add_f32 v[138:139], v[138:139], 1.0 op_sel_hi:[1,0]
	v_pk_add_f32 v[142:143], v[142:143], 1.0 op_sel_hi:[1,0]
	v_pk_add_f32 v[140:141], v[140:141], 1.0 op_sel_hi:[1,0]
	v_pk_add_f32 v[144:145], v[144:145], 1.0 op_sel_hi:[1,0]
	v_rcp_f32_e32 v138, v138
	v_rcp_f32_e32 v139, v139
	v_rcp_f32_e32 v142, v142
	v_rcp_f32_e32 v143, v143
	v_rcp_f32_e32 v140, v140
	v_rcp_f32_e32 v141, v141
	v_rcp_f32_e32 v144, v144
	v_rcp_f32_e32 v145, v145
	s_nop 0
	v_pk_mul_f32 v[138:139], v[134:135], v[138:139]
	v_pk_mul_f32 v[142:143], v[130:131], v[142:143]
	v_pk_mul_f32 v[140:141], v[136:137], v[140:141]
	v_pk_mul_f32 v[144:145], v[132:133], v[144:145]

.LBB0_142:
	v_pk_mul_f32 v[130:131], v[126:127], s[98:99]
	v_pk_mul_f32 v[132:133], v[122:123], s[98:99]
	v_pk_mul_f32 v[134:135], v[128:129], s[98:99]
	v_pk_mul_f32 v[136:137], v[124:125], s[98:99]
	v_exp_f32_e32 v130, v130
	v_exp_f32_e32 v131, v131
	v_exp_f32_e32 v132, v132
	v_exp_f32_e32 v133, v133
	v_exp_f32_e32 v134, v134
	v_exp_f32_e32 v135, v135
	v_exp_f32_e32 v136, v136
	v_exp_f32_e32 v137, v137
	v_pk_add_f32 v[130:131], v[130:131], 1.0 op_sel_hi:[1,0]
	v_pk_add_f32 v[132:133], v[132:133], 1.0 op_sel_hi:[1,0]
	v_pk_add_f32 v[134:135], v[134:135], 1.0 op_sel_hi:[1,0]
	v_pk_add_f32 v[136:137], v[136:137], 1.0 op_sel_hi:[1,0]
	v_rcp_f32_e32 v130, v130
	v_rcp_f32_e32 v131, v131
	v_rcp_f32_e32 v132, v132
	v_rcp_f32_e32 v133, v133
	v_rcp_f32_e32 v134, v134
	v_rcp_f32_e32 v135, v135
	v_rcp_f32_e32 v136, v136
	v_rcp_f32_e32 v137, v137
	s_nop 0
	v_pk_mul_f32 v[150:151], v[126:127], v[130:131]
	v_pk_mul_f32 v[174:175], v[122:123], v[132:133]
	v_pk_mul_f32 v[152:153], v[128:129], v[134:135]
	v_pk_mul_f32 v[176:177], v[124:125], v[136:137]

.LBB0_162:
	s_andn2_b64 vcc, exec, s[20:21]
	s_cbranch_vccnz .LBB0_164
	v_pk_mul_f32 v[122:123], v[118:119], s[98:99]
	v_pk_mul_f32 v[126:127], v[114:115], s[98:99]
	v_pk_mul_f32 v[124:125], v[120:121], s[98:99]
	v_pk_mul_f32 v[128:129], v[116:117], s[98:99]
	v_exp_f32_e32 v122, v122
	v_exp_f32_e32 v123, v123
	v_exp_f32_e32 v126, v126
	v_exp_f32_e32 v127, v127
	v_exp_f32_e32 v124, v124
	v_exp_f32_e32 v125, v125
	v_exp_f32_e32 v128, v128
	v_exp_f32_e32 v129, v129
	v_pk_add_f32 v[122:123], v[122:123], 1.0 op_sel_hi:[1,0]
	v_pk_add_f32 v[126:127], v[126:127], 1.0 op_sel_hi:[1,0]
	v_pk_add_f32 v[124:125], v[124:125], 1.0 op_sel_hi:[1,0]
	v_pk_add_f32 v[128:129], v[128:129], 1.0 op_sel_hi:[1,0]
	v_rcp_f32_e32 v122, v122
	v_rcp_f32_e32 v123, v123
	v_rcp_f32_e32 v126, v126
	v_rcp_f32_e32 v127, v127
	v_rcp_f32_e32 v124, v124
	v_rcp_f32_e32 v125, v125
	v_rcp_f32_e32 v128, v128
	v_rcp_f32_e32 v129, v129
	s_nop 0
	v_pk_mul_f32 v[122:123], v[118:119], v[122:123]
	v_pk_mul_f32 v[126:127], v[114:115], v[126:127]
	v_pk_mul_f32 v[124:125], v[120:121], v[124:125]
	v_pk_mul_f32 v[128:129], v[116:117], v[128:129]

.LBB0_192:
	v_pk_mul_f32 v[114:115], v[110:111], s[98:99]
	v_pk_mul_f32 v[116:117], v[106:107], s[98:99]
	v_pk_mul_f32 v[118:119], v[112:113], s[98:99]
	v_pk_mul_f32 v[120:121], v[108:109], s[98:99]
	v_exp_f32_e32 v114, v114
	v_exp_f32_e32 v115, v115
	v_exp_f32_e32 v116, v116
	v_exp_f32_e32 v117, v117
	v_exp_f32_e32 v118, v118
	v_exp_f32_e32 v119, v119
	v_exp_f32_e32 v120, v120
	v_exp_f32_e32 v121, v121
	v_pk_add_f32 v[114:115], v[114:115], 1.0 op_sel_hi:[1,0]
	v_pk_add_f32 v[116:117], v[116:117], 1.0 op_sel_hi:[1,0]
	v_pk_add_f32 v[118:119], v[118:119], 1.0 op_sel_hi:[1,0]
	v_pk_add_f32 v[120:121], v[120:121], 1.0 op_sel_hi:[1,0]
	v_rcp_f32_e32 v114, v114
	v_rcp_f32_e32 v115, v115
	v_rcp_f32_e32 v116, v116
	v_rcp_f32_e32 v117, v117
	v_rcp_f32_e32 v118, v118
	v_rcp_f32_e32 v119, v119
	v_rcp_f32_e32 v120, v120
	v_rcp_f32_e32 v121, v121
	s_nop 0
	v_pk_mul_f32 v[130:131], v[110:111], v[114:115]
	v_pk_mul_f32 v[134:135], v[106:107], v[116:117]
	v_pk_mul_f32 v[132:133], v[112:113], v[118:119]
	v_pk_mul_f32 v[136:137], v[108:109], v[120:121]

.LBB0_212:
	s_andn2_b64 vcc, exec, s[20:21]
	s_cbranch_vccnz .LBB0_214
	v_pk_mul_f32 v[106:107], v[102:103], s[98:99]
	v_pk_mul_f32 v[110:111], v[98:99], s[98:99]
	v_pk_mul_f32 v[108:109], v[104:105], s[98:99]
	v_pk_mul_f32 v[112:113], v[100:101], s[98:99]
	v_exp_f32_e32 v106, v106
	v_exp_f32_e32 v107, v107
	v_exp_f32_e32 v110, v110
	v_exp_f32_e32 v111, v111
	v_exp_f32_e32 v108, v108
	v_exp_f32_e32 v109, v109
	v_exp_f32_e32 v112, v112
	v_exp_f32_e32 v113, v113
	v_pk_add_f32 v[106:107], v[106:107], 1.0 op_sel_hi:[1,0]
	v_pk_add_f32 v[110:111], v[110:111], 1.0 op_sel_hi:[1,0]
	v_pk_add_f32 v[108:109], v[108:109], 1.0 op_sel_hi:[1,0]
	v_pk_add_f32 v[112:113], v[112:113], 1.0 op_sel_hi:[1,0]
	v_rcp_f32_e32 v106, v106
	v_rcp_f32_e32 v107, v107
	v_rcp_f32_e32 v110, v110
	v_rcp_f32_e32 v111, v111
	v_rcp_f32_e32 v108, v108
	v_rcp_f32_e32 v109, v109
	v_rcp_f32_e32 v112, v112
	v_rcp_f32_e32 v113, v113
	s_nop 0
	v_pk_mul_f32 v[106:107], v[102:103], v[106:107]
	v_pk_mul_f32 v[110:111], v[98:99], v[110:111]
	v_pk_mul_f32 v[108:109], v[104:105], v[108:109]
	v_pk_mul_f32 v[112:113], v[100:101], v[112:113]

.LBB0_242:
	v_pk_mul_f32 v[98:99], v[94:95], s[98:99]
	v_pk_mul_f32 v[100:101], v[90:91], s[98:99]
	v_pk_mul_f32 v[102:103], v[96:97], s[98:99]
	v_pk_mul_f32 v[104:105], v[92:93], s[98:99]
	v_exp_f32_e32 v98, v98
	v_exp_f32_e32 v99, v99
	v_exp_f32_e32 v100, v100
	v_exp_f32_e32 v101, v101
	v_exp_f32_e32 v102, v102
	v_exp_f32_e32 v103, v103
	v_exp_f32_e32 v104, v104
	v_exp_f32_e32 v105, v105
	v_pk_add_f32 v[98:99], v[98:99], 1.0 op_sel_hi:[1,0]
	v_pk_add_f32 v[100:101], v[100:101], 1.0 op_sel_hi:[1,0]
	v_pk_add_f32 v[102:103], v[102:103], 1.0 op_sel_hi:[1,0]
	v_pk_add_f32 v[104:105], v[104:105], 1.0 op_sel_hi:[1,0]
	v_rcp_f32_e32 v98, v98
	v_rcp_f32_e32 v99, v99
	v_rcp_f32_e32 v100, v100
	v_rcp_f32_e32 v101, v101
	v_rcp_f32_e32 v102, v102
	v_rcp_f32_e32 v103, v103
	v_rcp_f32_e32 v104, v104
	v_rcp_f32_e32 v105, v105
	s_nop 0
	v_pk_mul_f32 v[114:115], v[94:95], v[98:99]
	v_pk_mul_f32 v[118:119], v[90:91], v[100:101]
	v_pk_mul_f32 v[116:117], v[96:97], v[102:103]
	v_pk_mul_f32 v[120:121], v[92:93], v[104:105]

.LBB0_262:
	s_andn2_b64 vcc, exec, s[20:21]
	s_cbranch_vccnz .LBB0_264
	v_pk_mul_f32 v[90:91], v[86:87], s[98:99]
	v_pk_mul_f32 v[94:95], v[82:83], s[98:99]
	v_pk_mul_f32 v[92:93], v[88:89], s[98:99]
	v_pk_mul_f32 v[96:97], v[84:85], s[98:99]
	v_exp_f32_e32 v90, v90
	v_exp_f32_e32 v91, v91
	v_exp_f32_e32 v94, v94
	v_exp_f32_e32 v95, v95
	v_exp_f32_e32 v92, v92
	v_exp_f32_e32 v93, v93
	v_exp_f32_e32 v96, v96
	v_exp_f32_e32 v97, v97
	v_pk_add_f32 v[90:91], v[90:91], 1.0 op_sel_hi:[1,0]
	v_pk_add_f32 v[94:95], v[94:95], 1.0 op_sel_hi:[1,0]
	v_pk_add_f32 v[92:93], v[92:93], 1.0 op_sel_hi:[1,0]
	v_pk_add_f32 v[96:97], v[96:97], 1.0 op_sel_hi:[1,0]
	v_rcp_f32_e32 v90, v90
	v_rcp_f32_e32 v91, v91
	v_rcp_f32_e32 v94, v94
	v_rcp_f32_e32 v95, v95
	v_rcp_f32_e32 v92, v92
	v_rcp_f32_e32 v93, v93
	v_rcp_f32_e32 v96, v96
	v_rcp_f32_e32 v97, v97
	s_nop 0
	v_pk_mul_f32 v[90:91], v[86:87], v[90:91]
	v_pk_mul_f32 v[94:95], v[82:83], v[94:95]
	v_pk_mul_f32 v[92:93], v[88:89], v[92:93]
	v_pk_mul_f32 v[96:97], v[84:85], v[96:97]

.LBB0_292:
	v_pk_mul_f32 v[82:83], v[78:79], s[98:99]
	v_pk_mul_f32 v[84:85], v[74:75], s[98:99]
	v_pk_mul_f32 v[86:87], v[80:81], s[98:99]
	v_pk_mul_f32 v[88:89], v[76:77], s[98:99]
	v_exp_f32_e32 v82, v82
	v_exp_f32_e32 v83, v83
	v_exp_f32_e32 v84, v84
	v_exp_f32_e32 v85, v85
	v_exp_f32_e32 v86, v86
	v_exp_f32_e32 v87, v87
	v_exp_f32_e32 v88, v88
	v_exp_f32_e32 v89, v89
	v_pk_add_f32 v[82:83], v[82:83], 1.0 op_sel_hi:[1,0]
	v_pk_add_f32 v[84:85], v[84:85], 1.0 op_sel_hi:[1,0]
	v_pk_add_f32 v[86:87], v[86:87], 1.0 op_sel_hi:[1,0]
	v_pk_add_f32 v[88:89], v[88:89], 1.0 op_sel_hi:[1,0]
	v_rcp_f32_e32 v82, v82
	v_rcp_f32_e32 v83, v83
	v_rcp_f32_e32 v84, v84
	v_rcp_f32_e32 v85, v85
	v_rcp_f32_e32 v86, v86
	v_rcp_f32_e32 v87, v87
	v_rcp_f32_e32 v88, v88
	v_rcp_f32_e32 v89, v89
	s_nop 0
	v_pk_mul_f32 v[98:99], v[78:79], v[82:83]
	v_pk_mul_f32 v[102:103], v[74:75], v[84:85]
	v_pk_mul_f32 v[100:101], v[80:81], v[86:87]
	v_pk_mul_f32 v[104:105], v[76:77], v[88:89]

.LBB0_312:
	s_andn2_b64 vcc, exec, s[20:21]
	s_cbranch_vccnz .LBB0_314
	v_pk_mul_f32 v[74:75], v[70:71], s[98:99]
	v_pk_mul_f32 v[78:79], v[66:67], s[98:99]
	v_pk_mul_f32 v[76:77], v[72:73], s[98:99]
	v_pk_mul_f32 v[80:81], v[68:69], s[98:99]
	v_exp_f32_e32 v74, v74
	v_exp_f32_e32 v75, v75
	v_exp_f32_e32 v78, v78
	v_exp_f32_e32 v79, v79
	v_exp_f32_e32 v76, v76
	v_exp_f32_e32 v77, v77
	v_exp_f32_e32 v80, v80
	v_exp_f32_e32 v81, v81
	v_pk_add_f32 v[74:75], v[74:75], 1.0 op_sel_hi:[1,0]
	v_pk_add_f32 v[78:79], v[78:79], 1.0 op_sel_hi:[1,0]
	v_pk_add_f32 v[76:77], v[76:77], 1.0 op_sel_hi:[1,0]
	v_pk_add_f32 v[80:81], v[80:81], 1.0 op_sel_hi:[1,0]
	v_rcp_f32_e32 v74, v74
	v_rcp_f32_e32 v75, v75
	v_rcp_f32_e32 v78, v78
	v_rcp_f32_e32 v79, v79
	v_rcp_f32_e32 v76, v76
	v_rcp_f32_e32 v77, v77
	v_rcp_f32_e32 v80, v80
	v_rcp_f32_e32 v81, v81
	s_nop 0
	v_pk_mul_f32 v[74:75], v[70:71], v[74:75]
	v_pk_mul_f32 v[78:79], v[66:67], v[78:79]
	v_pk_mul_f32 v[76:77], v[72:73], v[76:77]
	v_pk_mul_f32 v[80:81], v[68:69], v[80:81]

.LBB0_342:
	v_pk_mul_f32 v[66:67], v[62:63], s[98:99]
	v_pk_mul_f32 v[68:69], v[58:59], s[98:99]
	v_pk_mul_f32 v[70:71], v[64:65], s[98:99]
	v_pk_mul_f32 v[72:73], v[60:61], s[98:99]
	v_exp_f32_e32 v66, v66
	v_exp_f32_e32 v67, v67
	v_exp_f32_e32 v68, v68
	v_exp_f32_e32 v69, v69
	v_exp_f32_e32 v70, v70
	v_exp_f32_e32 v71, v71
	v_exp_f32_e32 v72, v72
	v_exp_f32_e32 v73, v73
	v_pk_add_f32 v[66:67], v[66:67], 1.0 op_sel_hi:[1,0]
	v_pk_add_f32 v[68:69], v[68:69], 1.0 op_sel_hi:[1,0]
	v_pk_add_f32 v[70:71], v[70:71], 1.0 op_sel_hi:[1,0]
	v_pk_add_f32 v[72:73], v[72:73], 1.0 op_sel_hi:[1,0]
	v_rcp_f32_e32 v66, v66
	v_rcp_f32_e32 v67, v67
	v_rcp_f32_e32 v68, v68
	v_rcp_f32_e32 v69, v69
	v_rcp_f32_e32 v70, v70
	v_rcp_f32_e32 v71, v71
	v_rcp_f32_e32 v72, v72
	v_rcp_f32_e32 v73, v73
	s_nop 0
	v_pk_mul_f32 v[82:83], v[62:63], v[66:67]
	v_pk_mul_f32 v[86:87], v[58:59], v[68:69]
	v_pk_mul_f32 v[84:85], v[64:65], v[70:71]
	v_pk_mul_f32 v[88:89], v[60:61], v[72:73]

.LBB0_362:
	s_andn2_b64 vcc, exec, s[20:21]
	s_cbranch_vccnz .LBB0_364
	v_pk_mul_f32 v[58:59], v[54:55], s[98:99]
	v_pk_mul_f32 v[62:63], v[50:51], s[98:99]
	v_pk_mul_f32 v[60:61], v[56:57], s[98:99]
	v_pk_mul_f32 v[64:65], v[52:53], s[98:99]
	v_exp_f32_e32 v58, v58
	v_exp_f32_e32 v59, v59
	v_exp_f32_e32 v62, v62
	v_exp_f32_e32 v63, v63
	v_exp_f32_e32 v60, v60
	v_exp_f32_e32 v61, v61
	v_exp_f32_e32 v64, v64
	v_exp_f32_e32 v65, v65
	v_pk_add_f32 v[58:59], v[58:59], 1.0 op_sel_hi:[1,0]
	v_pk_add_f32 v[62:63], v[62:63], 1.0 op_sel_hi:[1,0]
	v_pk_add_f32 v[60:61], v[60:61], 1.0 op_sel_hi:[1,0]
	v_pk_add_f32 v[64:65], v[64:65], 1.0 op_sel_hi:[1,0]
	v_rcp_f32_e32 v58, v58
	v_rcp_f32_e32 v59, v59
	v_rcp_f32_e32 v62, v62
	v_rcp_f32_e32 v63, v63
	v_rcp_f32_e32 v60, v60
	v_rcp_f32_e32 v61, v61
	v_rcp_f32_e32 v64, v64
	v_rcp_f32_e32 v65, v65
	s_nop 0
	v_pk_mul_f32 v[58:59], v[54:55], v[58:59]
	v_pk_mul_f32 v[62:63], v[50:51], v[62:63]
	v_pk_mul_f32 v[60:61], v[56:57], v[60:61]
	v_pk_mul_f32 v[64:65], v[52:53], v[64:65]

.LBB0_392:
	v_pk_mul_f32 v[50:51], v[46:47], s[98:99]
	v_pk_mul_f32 v[52:53], v[42:43], s[98:99]
	v_pk_mul_f32 v[54:55], v[48:49], s[98:99]
	v_pk_mul_f32 v[56:57], v[44:45], s[98:99]
	v_exp_f32_e32 v50, v50
	v_exp_f32_e32 v51, v51
	v_exp_f32_e32 v52, v52
	v_exp_f32_e32 v53, v53
	v_exp_f32_e32 v54, v54
	v_exp_f32_e32 v55, v55
	v_exp_f32_e32 v56, v56
	v_exp_f32_e32 v57, v57
	v_pk_add_f32 v[50:51], v[50:51], 1.0 op_sel_hi:[1,0]
	v_pk_add_f32 v[52:53], v[52:53], 1.0 op_sel_hi:[1,0]
	v_pk_add_f32 v[54:55], v[54:55], 1.0 op_sel_hi:[1,0]
	v_pk_add_f32 v[56:57], v[56:57], 1.0 op_sel_hi:[1,0]
	v_rcp_f32_e32 v50, v50
	v_rcp_f32_e32 v51, v51
	v_rcp_f32_e32 v52, v52
	v_rcp_f32_e32 v53, v53
	v_rcp_f32_e32 v54, v54
	v_rcp_f32_e32 v55, v55
	v_rcp_f32_e32 v56, v56
	v_rcp_f32_e32 v57, v57
	s_nop 0
	v_pk_mul_f32 v[58:59], v[46:47], v[50:51]
	v_pk_mul_f32 v[70:71], v[42:43], v[52:53]
	v_pk_mul_f32 v[68:69], v[48:49], v[54:55]
	v_pk_mul_f32 v[72:73], v[44:45], v[56:57]

.LBB0_412:
	s_andn2_b64 vcc, exec, s[20:21]
	s_cbranch_vccnz .LBB0_414
	v_pk_mul_f32 v[42:43], v[30:31], s[98:99]
	v_pk_mul_f32 v[46:47], v[26:27], s[98:99]
	v_pk_mul_f32 v[44:45], v[32:33], s[98:99]
	v_pk_mul_f32 v[48:49], v[28:29], s[98:99]
	v_exp_f32_e32 v42, v42
	v_exp_f32_e32 v43, v43
	v_exp_f32_e32 v46, v46
	v_exp_f32_e32 v47, v47
	v_exp_f32_e32 v44, v44
	v_exp_f32_e32 v45, v45
	v_exp_f32_e32 v48, v48
	v_exp_f32_e32 v49, v49
	v_pk_add_f32 v[42:43], v[42:43], 1.0 op_sel_hi:[1,0]
	v_pk_add_f32 v[46:47], v[46:47], 1.0 op_sel_hi:[1,0]
	v_pk_add_f32 v[44:45], v[44:45], 1.0 op_sel_hi:[1,0]
	v_pk_add_f32 v[48:49], v[48:49], 1.0 op_sel_hi:[1,0]
	v_rcp_f32_e32 v42, v42
	v_rcp_f32_e32 v43, v43
	v_rcp_f32_e32 v46, v46
	v_rcp_f32_e32 v47, v47
	v_rcp_f32_e32 v44, v44
	v_rcp_f32_e32 v45, v45
	v_rcp_f32_e32 v48, v48
	v_rcp_f32_e32 v49, v49
	s_nop 0
	v_pk_mul_f32 v[42:43], v[30:31], v[42:43]
	v_pk_mul_f32 v[46:47], v[26:27], v[46:47]
	v_pk_mul_f32 v[44:45], v[32:33], v[44:45]
	v_pk_mul_f32 v[48:49], v[28:29], v[48:49]

.LBB0_442:
	v_pk_mul_f32 v[26:27], v[14:15], s[98:99]
	v_pk_mul_f32 v[28:29], v[10:11], s[98:99]
	v_pk_mul_f32 v[30:31], v[16:17], s[98:99]
	v_pk_mul_f32 v[32:33], v[12:13], s[98:99]
	v_exp_f32_e32 v26, v26
	v_exp_f32_e32 v27, v27
	v_exp_f32_e32 v28, v28
	v_exp_f32_e32 v29, v29
	v_exp_f32_e32 v30, v30
	v_exp_f32_e32 v31, v31
	v_exp_f32_e32 v32, v32
	v_exp_f32_e32 v33, v33
	v_pk_add_f32 v[26:27], v[26:27], 1.0 op_sel_hi:[1,0]
	v_pk_add_f32 v[28:29], v[28:29], 1.0 op_sel_hi:[1,0]
	v_pk_add_f32 v[30:31], v[30:31], 1.0 op_sel_hi:[1,0]
	v_pk_add_f32 v[32:33], v[32:33], 1.0 op_sel_hi:[1,0]
	v_rcp_f32_e32 v26, v26
	v_rcp_f32_e32 v27, v27
	v_rcp_f32_e32 v28, v28
	v_rcp_f32_e32 v29, v29
	v_rcp_f32_e32 v30, v30
	v_rcp_f32_e32 v31, v31
	v_rcp_f32_e32 v32, v32
	v_rcp_f32_e32 v33, v33
	s_nop 0
	v_pk_mul_f32 v[48:49], v[14:15], v[26:27]
	v_pk_mul_f32 v[52:53], v[10:11], v[28:29]
	v_pk_mul_f32 v[50:51], v[16:17], v[30:31]
	v_pk_mul_f32 v[54:55], v[12:13], v[32:33]

.LBB0_462:
	s_andn2_b64 vcc, exec, s[4:5]
	s_cbranch_vccnz .LBB0_464
	v_pk_mul_f32 v[10:11], v[6:7], s[98:99]
	v_pk_mul_f32 v[14:15], v[2:3], s[98:99]
	v_pk_mul_f32 v[12:13], v[8:9], s[98:99]
	v_pk_mul_f32 v[16:17], v[4:5], s[98:99]
	v_exp_f32_e32 v10, v10
	v_exp_f32_e32 v11, v11
	v_exp_f32_e32 v14, v14
	v_exp_f32_e32 v15, v15
	v_exp_f32_e32 v12, v12
	v_exp_f32_e32 v13, v13
	v_exp_f32_e32 v16, v16
	v_exp_f32_e32 v17, v17
	v_pk_add_f32 v[10:11], v[10:11], 1.0 op_sel_hi:[1,0]
	v_pk_add_f32 v[14:15], v[14:15], 1.0 op_sel_hi:[1,0]
	v_pk_add_f32 v[12:13], v[12:13], 1.0 op_sel_hi:[1,0]
	v_pk_add_f32 v[16:17], v[16:17], 1.0 op_sel_hi:[1,0]
	v_rcp_f32_e32 v10, v10
	v_rcp_f32_e32 v11, v11
	v_rcp_f32_e32 v14, v14
	v_rcp_f32_e32 v15, v15
	v_rcp_f32_e32 v12, v12
	v_rcp_f32_e32 v13, v13
	v_rcp_f32_e32 v16, v16
	v_rcp_f32_e32 v17, v17
	s_nop 0
	v_pk_mul_f32 v[10:11], v[6:7], v[10:11]
	v_pk_mul_f32 v[14:15], v[2:3], v[14:15]
	v_pk_mul_f32 v[12:13], v[8:9], v[12:13]
	v_pk_mul_f32 v[16:17], v[4:5], v[16:17]
